# UP passes (owner and helpers) with an 8-deep B prefetch ring: helper passes run nearly alone and are latency-bound
# baseline (speedup 1.0000x reference)
; DI void lds_barrier() { asm volatile("s_waitcnt lgkmcnt(0)\n\ts_barrier" ::: "memory"); }
;     ...
;     for (int pass = 0; pass * NWAVE < NU; ++pass) {
;         const int unit = pass * NWAVE + wave;
;         const bool active = unit < NU;
;         const int ucl = active ? unit : NU - 1;
;         const u32x4* bp = Bw + (size_t)(ucl * NT) * 64 + lane;
;         const size_t kstr = (size_t)NU * NT * 64;
;         f32x16 acc[MT][NT];
; #pragma unroll
;         for (int mi = 0; mi < MT; ++mi)
; #pragma unroll
;             for (int nj = 0; nj < NT; ++nj)
; #pragma unroll
;                 for (int i = 0; i < 16; ++i) acc[mi][nj][i] = 0.f;
;         u32x4 bq[PD][NT];
; #pragma unroll
;         for (int s = 0; s < PD; ++s)
; #pragma unroll
;             for (int j = 0; j < NT; ++j) bq[s][j] = bp[(size_t)s * kstr + j * 64];
;         u32x4 areg[MT];
;         if (pass == 0) __syncthreads();
; #pragma unroll
;         for (int i = 0; i < MT; ++i) { const int idx = i * NTHR + tid, row = idx >> 4, seg = idx & 15; areg[i] = *(const u32x4*)(A + ((row + (i == 2 ? d2 : 0)) * lda + seg * 8)); }
; #pragma unroll
;         for (int i = 0; i < MT; ++i) { const int idx = i * NTHR + tid, row = idx >> 4, seg = idx & 15; *(u32x4*)(lds + row * A_LD + seg * 16) = areg[i]; }
;         lds_barrier();
.LBB0_461:
	global_load_dwordx4 v[112:115], v[158:159], off
	global_load_dwordx4 v[116:119], v[160:161], off
	global_load_dwordx4 v[120:123], v[162:163], off
	v_min_i32_e32 v16, 0x57, v232
	v_add_u32_e32 v50, v224, v226
	v_lshlrev_b32_e32 v48, 1, v16
	v_add_u32_e32 v51, v224, v227
	v_add_u32_e32 v52, v224, v228
	v_ashrrev_i32_e32 v49, 31, v48
	v_mov_b32_e32 v14, v1
	v_mov_b32_e32 v15, v1
	v_lshlrev_b64 v[48:49], 10, v[48:49]
	s_movk_i32 s0, 0x58
	v_mov_b32_e32 v0, v1
	v_mov_b32_e32 v2, v1
	v_mov_b32_e32 v3, v1
	v_mov_b32_e32 v4, v1
	v_mov_b32_e32 v5, v1
	v_mov_b32_e32 v6, v1
	v_mov_b32_e32 v7, v1
	v_mov_b32_e32 v8, v1
	v_mov_b32_e32 v9, v1
	v_mov_b32_e32 v10, v1
	v_mov_b32_e32 v11, v1
	v_mov_b32_e32 v12, v1
	v_mov_b32_e32 v13, v1
	v_mov_b64_e32 v[30:31], v[14:15]
	v_mov_b64_e32 v[46:47], v[14:15]
	v_lshl_add_u64 v[174:175], v[164:165], 0, v[48:49]
	v_mov_b64_e32 v[78:79], v[14:15]
	v_mov_b64_e32 v[94:95], v[14:15]
	v_mov_b64_e32 v[110:111], v[14:15]
	v_cmp_gt_i32_e64 s[4:5], s0, v233
	s_mov_b32 s37, 0
	s_mov_b64 s[0:1], 0
	s_mov_b32 s52, 7
	v_mov_b32_e32 v168, v231
	v_mov_b32_e32 v170, v230
	v_mov_b32_e32 v172, v229
	v_mov_b64_e32 v[28:29], v[12:13]
	v_mov_b64_e32 v[26:27], v[10:11]
	v_mov_b64_e32 v[24:25], v[8:9]
	v_mov_b64_e32 v[22:23], v[6:7]
	v_mov_b64_e32 v[20:21], v[4:5]
	v_mov_b64_e32 v[18:19], v[2:3]
	v_mov_b64_e32 v[16:17], v[0:1]
	v_mov_b64_e32 v[44:45], v[12:13]
	v_mov_b64_e32 v[42:43], v[10:11]
	v_mov_b64_e32 v[40:41], v[8:9]
	v_mov_b64_e32 v[38:39], v[6:7]
	v_mov_b64_e32 v[36:37], v[4:5]
	v_mov_b64_e32 v[34:35], v[2:3]
	v_mov_b64_e32 v[32:33], v[0:1]
	v_mov_b64_e32 v[76:77], v[12:13]
	v_mov_b64_e32 v[74:75], v[10:11]
	v_mov_b64_e32 v[72:73], v[8:9]
	v_mov_b64_e32 v[70:71], v[6:7]
	v_mov_b64_e32 v[68:69], v[4:5]
	v_mov_b64_e32 v[66:67], v[2:3]
	v_mov_b64_e32 v[64:65], v[0:1]
	v_mov_b64_e32 v[92:93], v[12:13]
	v_mov_b64_e32 v[90:91], v[10:11]
	v_mov_b64_e32 v[88:89], v[8:9]
	v_mov_b64_e32 v[86:87], v[6:7]
	v_mov_b64_e32 v[84:85], v[4:5]
	v_mov_b64_e32 v[82:83], v[2:3]
	v_mov_b64_e32 v[80:81], v[0:1]
	v_mov_b64_e32 v[108:109], v[12:13]
	v_mov_b64_e32 v[106:107], v[10:11]
	v_mov_b64_e32 v[104:105], v[8:9]
	v_mov_b64_e32 v[102:103], v[6:7]
	v_mov_b64_e32 v[100:101], v[4:5]
	v_mov_b64_e32 v[98:99], v[2:3]
	v_mov_b64_e32 v[96:97], v[0:1]
	s_waitcnt vmcnt(2)
	ds_write_b128 v50, v[112:115]
	s_waitcnt vmcnt(1)
	ds_write_b128 v51, v[116:119]
	s_waitcnt vmcnt(0)
	ds_write_b128 v52, v[120:123]
	s_waitcnt lgkmcnt(0)
	s_barrier
	v_mov_b64_e32 v[62:63], v[14:15]
	v_mov_b64_e32 v[60:61], v[12:13]
	v_mov_b64_e32 v[58:59], v[10:11]
	v_mov_b64_e32 v[56:57], v[8:9]
	v_mov_b64_e32 v[54:55], v[6:7]
	v_mov_b64_e32 v[52:53], v[4:5]
	v_mov_b64_e32 v[50:51], v[2:3]
	v_mov_b64_e32 v[48:49], v[0:1]
	s_mov_b32 s101, 0
	s_mov_b32 s100, 0xb0000
	v_lshl_add_u64 v[234:235], v[166:167], 0, s[100:101]
	global_load_dwordx4 v[192:195], v[234:235], off
	global_load_dwordx4 v[196:199], v[234:235], off offset:1024
	s_mov_b32 s100, 0xdc000
	v_lshl_add_u64 v[234:235], v[166:167], 0, s[100:101]
	global_load_dwordx4 v[200:203], v[234:235], off
	global_load_dwordx4 v[204:207], v[234:235], off offset:1024
	s_mov_b32 s100, 0x108000
	v_lshl_add_u64 v[234:235], v[166:167], 0, s[100:101]
	global_load_dwordx4 v[208:211], v[234:235], off
	global_load_dwordx4 v[212:215], v[234:235], off offset:1024
	s_mov_b32 s100, 0x134000
	v_lshl_add_u64 v[234:235], v[166:167], 0, s[100:101]
	global_load_dwordx4 v[216:219], v[234:235], off
	global_load_dwordx4 v[236:239], v[234:235], off offset:1024
	s_branch .LBB0_463

; #define MFMA32(a, b, c) __builtin_amdgcn_mfma_f32_32x32x16_f16((a), (b), (c), 0, 0, 0)
;     ...
;         for (int c = 0; c < NCH; ++c) {
;             if (c + 1 < NCH) {
; #pragma unroll
;                 for (int i = 0; i < MT; ++i) { const int idx = i * NTHR + tid, row = idx >> 4, seg = idx & 15; areg[i] = *(const u32x4*)(A + ((row + (i == 2 ? d2 : 0)) * lda + (c + 1) * A_CHUNK + seg * 8)); }
;             }
;             const unsigned char* ab = lds + (c & 1) * A_BUF + r * A_LD + 16 * h;
;             if (active) {
;                 bf16x8 a[MT], n[MT];
; #pragma unroll
;                 for (int mi = 0; mi < MT; ++mi) a[mi] = *(const bf16x8*)(ab + mi * 32 * A_LD);
; #pragma unroll
;                 for (int ks = 0; ks < A_CHUNK / 16; ++ks) {
; #pragma unroll
;                     for (int mi = 0; mi < MT; ++mi) n[mi] = a[mi];
;                     if (ks + 1 < A_CHUNK / 16) {
; #pragma unroll
;                         for (int mi = 0; mi < MT; ++mi) n[mi] = *(const bf16x8*)(ab + mi * 32 * A_LD + (ks + 1) * 32);
;                     }
; #pragma unroll
;                     for (int j = 0; j < NT; ++j)
; #pragma unroll
;                         for (int mi = 0; mi < MT; ++mi) acc[mi][j] = MFMA32(a[mi], __builtin_bit_cast(bf16x8, bq[ks % PD][j]), acc[mi][j]);
;                     int nk = c * (A_CHUNK / 16) + ks + PD; nk = nk < KS ? nk : KS - 1;
; #pragma unroll
;                     for (int j = 0; j < NT; ++j) { if (XM == 0) bq[ks % PD][j] = bp[(size_t)nk * kstr + j * 64]; else if (XM == 1) bq[ks % PD][j] = bp[(size_t)(nk & 7) * 128 + j * 64]; }
;                     __builtin_amdgcn_sched_barrier(0);
; #pragma unroll
;                     for (int mi = 0; mi < MT; ++mi) a[mi] = n[mi];
;                 }
.LBB0_467:
	s_bitcmp1_b32 s37, 0
	s_cselect_b32 s53, 0x6600, 0
	v_add_u32_e32 v0, s53, v225
	ds_read_b128 v[2:5], v0
	ds_read_b128 v[6:9], v0 offset:8704
	ds_read_b128 v[10:13], v0 offset:17408
	ds_read_b128 v[240:243], v0 offset:32
	ds_read_b128 v[244:247], v0 offset:8736
	ds_read_b128 v[248:251], v0 offset:17440
	s_waitcnt vmcnt(15) lgkmcnt(3)
	v_mfma_f32_32x32x16_f16 v[96:111], v[2:5], v[152:155], v[96:111]
	v_mfma_f32_32x32x16_f16 v[64:79], v[6:9], v[152:155], v[64:79]
	v_mfma_f32_32x32x16_f16 v[32:47], v[10:13], v[152:155], v[32:47]
	s_waitcnt vmcnt(14)
	v_mfma_f32_32x32x16_f16 v[80:95], v[2:5], v[124:127], v[80:95]
	v_mfma_f32_32x32x16_f16 v[48:63], v[6:9], v[124:127], v[48:63]
	v_mfma_f32_32x32x16_f16 v[16:31], v[10:13], v[124:127], v[16:31]
	s_add_i32 s53, s52, 1
	s_min_u32 s53, s53, 63
	s_mul_i32 s100, s53, 0x2c000
	v_lshl_add_u64 v[234:235], v[166:167], 0, s[100:101]
	global_load_dwordx4 v[152:155], v[234:235], off
	global_load_dwordx4 v[124:127], v[234:235], off offset:1024
	ds_read_b128 v[2:5], v0 offset:64
	ds_read_b128 v[6:9], v0 offset:8768
	ds_read_b128 v[10:13], v0 offset:17472
	s_waitcnt vmcnt(15) lgkmcnt(3)
	v_mfma_f32_32x32x16_f16 v[96:111], v[240:243], v[140:143], v[96:111]
	v_mfma_f32_32x32x16_f16 v[64:79], v[244:247], v[140:143], v[64:79]
	v_mfma_f32_32x32x16_f16 v[32:47], v[248:251], v[140:143], v[32:47]
	s_waitcnt vmcnt(14)
	v_mfma_f32_32x32x16_f16 v[80:95], v[240:243], v[128:131], v[80:95]
	v_mfma_f32_32x32x16_f16 v[48:63], v[244:247], v[128:131], v[48:63]
	v_mfma_f32_32x32x16_f16 v[16:31], v[248:251], v[128:131], v[16:31]
	s_add_i32 s53, s52, 2
	s_min_u32 s53, s53, 63
	s_mul_i32 s100, s53, 0x2c000
	v_lshl_add_u64 v[234:235], v[166:167], 0, s[100:101]
	global_load_dwordx4 v[140:143], v[234:235], off
	global_load_dwordx4 v[128:131], v[234:235], off offset:1024
	ds_read_b128 v[240:243], v0 offset:96
	ds_read_b128 v[244:247], v0 offset:8800
	ds_read_b128 v[248:251], v0 offset:17504
	s_waitcnt vmcnt(15) lgkmcnt(3)
	v_mfma_f32_32x32x16_f16 v[96:111], v[2:5], v[144:147], v[96:111]
	v_mfma_f32_32x32x16_f16 v[64:79], v[6:9], v[144:147], v[64:79]
	v_mfma_f32_32x32x16_f16 v[32:47], v[10:13], v[144:147], v[32:47]
	s_waitcnt vmcnt(14)
	v_mfma_f32_32x32x16_f16 v[80:95], v[2:5], v[132:135], v[80:95]
	v_mfma_f32_32x32x16_f16 v[48:63], v[6:9], v[132:135], v[48:63]
	v_mfma_f32_32x32x16_f16 v[16:31], v[10:13], v[132:135], v[16:31]
	s_add_i32 s53, s52, 3
	s_min_u32 s53, s53, 63
	s_mul_i32 s100, s53, 0x2c000
	v_lshl_add_u64 v[234:235], v[166:167], 0, s[100:101]
	global_load_dwordx4 v[144:147], v[234:235], off
	global_load_dwordx4 v[132:135], v[234:235], off offset:1024
	ds_read_b128 v[2:5], v0 offset:128
	ds_read_b128 v[6:9], v0 offset:8832
	ds_read_b128 v[10:13], v0 offset:17536
	s_waitcnt vmcnt(15) lgkmcnt(3)
	v_mfma_f32_32x32x16_f16 v[96:111], v[240:243], v[148:151], v[96:111]
	v_mfma_f32_32x32x16_f16 v[64:79], v[244:247], v[148:151], v[64:79]
	v_mfma_f32_32x32x16_f16 v[32:47], v[248:251], v[148:151], v[32:47]
	s_waitcnt vmcnt(14)
	v_mfma_f32_32x32x16_f16 v[80:95], v[240:243], v[136:139], v[80:95]
	v_mfma_f32_32x32x16_f16 v[48:63], v[244:247], v[136:139], v[48:63]
	v_mfma_f32_32x32x16_f16 v[16:31], v[248:251], v[136:139], v[16:31]
	s_add_i32 s53, s52, 4
	s_min_u32 s53, s53, 63
	s_mul_i32 s100, s53, 0x2c000
	v_lshl_add_u64 v[234:235], v[166:167], 0, s[100:101]
	global_load_dwordx4 v[148:151], v[234:235], off
	global_load_dwordx4 v[136:139], v[234:235], off offset:1024
	ds_read_b128 v[240:243], v0 offset:160
	ds_read_b128 v[244:247], v0 offset:8864
	ds_read_b128 v[248:251], v0 offset:17568
	s_waitcnt vmcnt(15) lgkmcnt(3)
	v_mfma_f32_32x32x16_f16 v[96:111], v[2:5], v[192:195], v[96:111]
	v_mfma_f32_32x32x16_f16 v[64:79], v[6:9], v[192:195], v[64:79]
	v_mfma_f32_32x32x16_f16 v[32:47], v[10:13], v[192:195], v[32:47]
	s_waitcnt vmcnt(14)
	v_mfma_f32_32x32x16_f16 v[80:95], v[2:5], v[196:199], v[80:95]
	v_mfma_f32_32x32x16_f16 v[48:63], v[6:9], v[196:199], v[48:63]
	v_mfma_f32_32x32x16_f16 v[16:31], v[10:13], v[196:199], v[16:31]
	s_add_i32 s53, s52, 5
	s_min_u32 s53, s53, 63
	s_mul_i32 s100, s53, 0x2c000
	v_lshl_add_u64 v[234:235], v[166:167], 0, s[100:101]
	global_load_dwordx4 v[192:195], v[234:235], off
	global_load_dwordx4 v[196:199], v[234:235], off offset:1024
	ds_read_b128 v[2:5], v0 offset:192
	ds_read_b128 v[6:9], v0 offset:8896
	ds_read_b128 v[10:13], v0 offset:17600
	s_waitcnt vmcnt(15) lgkmcnt(3)
	v_mfma_f32_32x32x16_f16 v[96:111], v[240:243], v[200:203], v[96:111]
	v_mfma_f32_32x32x16_f16 v[64:79], v[244:247], v[200:203], v[64:79]
	v_mfma_f32_32x32x16_f16 v[32:47], v[248:251], v[200:203], v[32:47]
	s_waitcnt vmcnt(14)
	v_mfma_f32_32x32x16_f16 v[80:95], v[240:243], v[204:207], v[80:95]
	v_mfma_f32_32x32x16_f16 v[48:63], v[244:247], v[204:207], v[48:63]
	v_mfma_f32_32x32x16_f16 v[16:31], v[248:251], v[204:207], v[16:31]
	s_add_i32 s53, s52, 6
	s_min_u32 s53, s53, 63
	s_mul_i32 s100, s53, 0x2c000
	v_lshl_add_u64 v[234:235], v[166:167], 0, s[100:101]
	global_load_dwordx4 v[200:203], v[234:235], off
	global_load_dwordx4 v[204:207], v[234:235], off offset:1024
	ds_read_b128 v[240:243], v0 offset:224
	ds_read_b128 v[244:247], v0 offset:8928
	ds_read_b128 v[248:251], v0 offset:17632
	s_waitcnt vmcnt(15) lgkmcnt(3)
	v_mfma_f32_32x32x16_f16 v[96:111], v[2:5], v[208:211], v[96:111]
	v_mfma_f32_32x32x16_f16 v[64:79], v[6:9], v[208:211], v[64:79]
	v_mfma_f32_32x32x16_f16 v[32:47], v[10:13], v[208:211], v[32:47]
	s_waitcnt vmcnt(14)
	v_mfma_f32_32x32x16_f16 v[80:95], v[2:5], v[212:215], v[80:95]
	v_mfma_f32_32x32x16_f16 v[48:63], v[6:9], v[212:215], v[48:63]
	v_mfma_f32_32x32x16_f16 v[16:31], v[10:13], v[212:215], v[16:31]
	s_add_i32 s53, s52, 7
	s_min_u32 s53, s53, 63
	s_mul_i32 s100, s53, 0x2c000
	v_lshl_add_u64 v[234:235], v[166:167], 0, s[100:101]
	global_load_dwordx4 v[208:211], v[234:235], off
	global_load_dwordx4 v[212:215], v[234:235], off offset:1024
	s_waitcnt vmcnt(15) lgkmcnt(0)
	v_mfma_f32_32x32x16_f16 v[96:111], v[240:243], v[216:219], v[96:111]
	v_mfma_f32_32x32x16_f16 v[64:79], v[244:247], v[216:219], v[64:79]
	v_mfma_f32_32x32x16_f16 v[32:47], v[248:251], v[216:219], v[32:47]
	s_waitcnt vmcnt(14)
	v_mfma_f32_32x32x16_f16 v[80:95], v[240:243], v[236:239], v[80:95]
	v_mfma_f32_32x32x16_f16 v[48:63], v[244:247], v[236:239], v[48:63]
	v_mfma_f32_32x32x16_f16 v[16:31], v[248:251], v[236:239], v[16:31]
	s_add_i32 s53, s52, 8
	s_min_u32 s53, s53, 63
	s_mul_i32 s100, s53, 0x2c000
	v_lshl_add_u64 v[234:235], v[166:167], 0, s[100:101]
	global_load_dwordx4 v[216:219], v[234:235], off
	global_load_dwordx4 v[236:239], v[234:235], off offset:1024
	s_or_b64 exec, exec, s[2:3]
	s_andn2_b64 vcc, exec, s[10:11]
	s_add_i32 s37, s37, 1
	s_cbranch_vccnz .LBB0_462

; DI const bf16_t* wp(const Params& p, int l, size_t off) { return (const bf16_t*)(p.ws + OFF_WP) + (size_t)l * PW_LAYER + off; }
; template <int MT> DI void phaseB(const Params& p, int l, int t, unsigned char* lds) {
;     ...
;     gemm64<1024, MT>(xb, DM, d2, wp(p, l, PW_UP), DFF2 / UW, lds, eu);
; }
.Lrup3_exit:
	v_mov_b32_e32 v192, 0x4200
	v_mov_b32_e32 v193, 0xb000
	v_mov_b32_e32 v194, 0xc600
	v_mov_b32_e32 v195, 0xdc00
	v_mov_b32_e32 v196, 0xf200
	v_mov_b32_e32 v197, 0x16000
	v_mov_b32_e32 v198, 0x17600
	v_mov_b32_e32 v199, 0x18c00
	v_mov_b32_e32 v200, 0x1a200
	v_mov_b32_e32 v201, 0x21000
	v_mov_b32_e32 v202, 0x22600
	v_mov_b32_e32 v203, 0x23c00
	v_mov_b32_e32 v204, 0x25200
	v_mov_b32_e32 v205, 0x2c000
	v_mov_b32_e32 v206, 0x2d600
	v_mov_b32_e32 v207, 0x2ec00
	v_mov_b32_e32 v208, 0x37000
	v_mov_b32_e32 v209, 0x39c00
	v_mov_b32_e32 v210, 0x3b200
	v_mov_b32_e32 v211, 0x42000
	v_mov_b32_e32 v212, 0x43600
	v_mov_b32_e32 v213, 0x44c00
	v_mov_b32_e32 v214, 0x46200
	v_mov_b32_e32 v215, 0x4d000
	v_mov_b32_e32 v216, 0x4e600
	v_mov_b32_e32 v217, 0x4fc00
	v_mov_b32_e32 v218, 0x51200
	s_branch .LBB0_312

; DI const bf16_t* wp(const Params& p, int l, size_t off) { return (const bf16_t*)(p.ws + OFF_WP) + (size_t)l * PW_LAYER + off; }
; template <int MT> DI void phaseB(const Params& p, int l, int t, unsigned char* lds) {
;     ...
;     gemm64<1024, MT>(xb, DM, d2, wp(p, l, PW_UP), DFF2 / UW, lds, eu);
; }
.Lhu_next:
	s_add_u32 s69, s69, 1
	s_cmp_lt_u32 s69, 4
	s_cbranch_scc1 .Lhu_target
	v_mov_b32_e32 v192, 0x4200
	v_mov_b32_e32 v193, 0xb000
	v_mov_b32_e32 v194, 0xc600
	v_mov_b32_e32 v195, 0xdc00
	v_mov_b32_e32 v196, 0xf200
	v_mov_b32_e32 v197, 0x16000
	v_mov_b32_e32 v198, 0x17600
	v_mov_b32_e32 v199, 0x18c00
	v_mov_b32_e32 v200, 0x1a200
	v_mov_b32_e32 v201, 0x21000
	v_mov_b32_e32 v202, 0x22600
	v_mov_b32_e32 v203, 0x23c00
	v_mov_b32_e32 v204, 0x25200
	v_mov_b32_e32 v205, 0x2c000
	v_mov_b32_e32 v206, 0x2d600
	v_mov_b32_e32 v207, 0x2ec00
	v_mov_b32_e32 v208, 0x37000
	v_mov_b32_e32 v209, 0x39c00
	v_mov_b32_e32 v210, 0x3b200
	v_mov_b32_e32 v211, 0x42000
	v_mov_b32_e32 v212, 0x43600
	v_mov_b32_e32 v213, 0x44c00
	v_mov_b32_e32 v214, 0x46200
	v_mov_b32_e32 v215, 0x4d000
	v_mov_b32_e32 v216, 0x4e600
	v_mov_b32_e32 v217, 0x4fc00
	v_mov_b32_e32 v218, 0x51200
	v_readlane_b32 s0, v180, 0
	v_readlane_b32 s1, v180, 1
	v_readlane_b32 s2, v180, 2
	v_readlane_b32 s3, v180, 3
	v_readlane_b32 s4, v180, 4
	v_readlane_b32 s5, v180, 5
	v_readlane_b32 s6, v180, 6
	v_readlane_b32 s7, v180, 7
	v_readlane_b32 s8, v180, 8
	v_readlane_b32 s9, v180, 9
	v_readlane_b32 s10, v180, 10
	v_readlane_b32 s11, v180, 11
	v_readlane_b32 s12, v180, 12
	v_readlane_b32 s13, v180, 13
	v_readlane_b32 s14, v180, 14
	v_readlane_b32 s15, v180, 15
	v_readlane_b32 s16, v180, 16
	v_readlane_b32 s17, v180, 17
	v_readlane_b32 s18, v180, 18
	v_readlane_b32 s19, v180, 19
	v_readlane_b32 s20, v180, 20
	v_readlane_b32 s21, v180, 21
	v_readlane_b32 s22, v180, 22
	v_readlane_b32 s23, v180, 23
	v_readlane_b32 s24, v180, 24
	v_readlane_b32 s25, v180, 25
	v_readlane_b32 s26, v180, 26
	v_readlane_b32 s27, v180, 27
	v_readlane_b32 s28, v180, 28
	v_readlane_b32 s29, v180, 29
	v_readlane_b32 s30, v180, 30
	v_readlane_b32 s31, v180, 31
	v_readlane_b32 s32, v180, 32
	v_readlane_b32 s33, v180, 33
	v_readlane_b32 s34, v180, 34
	v_readlane_b32 s35, v180, 35
	v_readlane_b32 s36, v180, 36
	v_readlane_b32 s37, v180, 37
	v_readlane_b32 s38, v180, 38
	v_readlane_b32 s39, v180, 39
	v_readlane_b32 s40, v180, 40
	v_readlane_b32 s41, v180, 41
	v_readlane_b32 s42, v180, 42
	v_readlane_b32 s43, v180, 43
	v_readlane_b32 s44, v180, 44
	v_readlane_b32 s45, v180, 45
	v_readlane_b32 s46, v180, 46
	v_readlane_b32 s47, v180, 47
	v_readlane_b32 s48, v180, 48
	v_readlane_b32 s49, v180, 49
	v_readlane_b32 s50, v180, 50
	v_readlane_b32 s51, v180, 51
	v_readlane_b32 s52, v180, 52
	v_readlane_b32 s53, v180, 53
	v_readlane_b32 s54, v180, 54
	v_readlane_b32 s55, v180, 55
	v_readlane_b32 s56, v180, 56
	v_readlane_b32 s57, v180, 57
	v_readlane_b32 s58, v180, 58
	v_readlane_b32 s59, v180, 59
	v_readlane_b32 s60, v180, 60
	v_readlane_b32 s61, v180, 61
	v_readlane_b32 s62, v180, 62
	v_readlane_b32 s63, v180, 63
	v_readlane_b32 s64, v181, 0
	v_readlane_b32 s65, v181, 1
	v_readlane_b32 s66, v181, 2
	v_readlane_b32 s67, v181, 3
	v_readlane_b32 s68, v181, 4
	v_readlane_b32 s69, v181, 5
	v_readlane_b32 s70, v181, 6
	v_readlane_b32 s71, v181, 7
	v_readlane_b32 s72, v181, 8
	v_readlane_b32 s73, v181, 9
	v_readlane_b32 s74, v181, 10
	v_readlane_b32 s75, v181, 11
	v_readlane_b32 s76, v181, 12
	v_readlane_b32 s77, v181, 13
	v_readlane_b32 s78, v181, 14
	v_readlane_b32 s79, v181, 15
	v_readlane_b32 s80, v181, 16
	v_readlane_b32 s81, v181, 17
	v_readlane_b32 s82, v181, 18
	v_readlane_b32 s83, v181, 19
	v_readlane_b32 s84, v181, 20
	v_readlane_b32 s85, v181, 21
	v_readlane_b32 s86, v181, 22
	v_readlane_b32 s87, v181, 23
	v_readlane_b32 s88, v181, 24
	v_readlane_b32 s89, v181, 25
	v_readlane_b32 s90, v181, 26
	v_readlane_b32 s91, v181, 27
	v_readlane_b32 s92, v181, 28
	v_readlane_b32 s93, v181, 29
	v_readlane_b32 s94, v181, 30
	v_readlane_b32 s95, v181, 31
	v_readlane_b32 s96, v181, 32
	v_readlane_b32 s97, v181, 33
	v_readlane_b32 s98, v181, 34
	v_readlane_b32 s99, v181, 35
	v_readlane_b32 s100, v181, 36
	v_readlane_b32 s101, v181, 37
	v_readlane_b32 vcc_lo, v181, 38
	v_readlane_b32 vcc_hi, v181, 39
